# v26: v4 plus the stacked safe scheduling edits (GEMM loop-edge barrier move, counted waits in norm loops, K0-only wait in attention prologue)
# baseline (speedup 1.0000x reference)
.LBB0_702:
	s_or_b64 exec, exec, s[20:21]
	v_mul_f32_e32 v54, 0x4b800000, v52
	v_cmp_gt_f32_e32 vcc, s23, v52
	s_add_u32 s25, s25, s14
	s_addc_u32 s26, s26, s15
	v_cndmask_b32_e32 v52, v52, v54, vcc
	v_rsq_f32_e32 v52, v52
	s_add_u32 s27, s27, s14
	s_addc_u32 s28, s28, s15
	v_lshl_add_u64 v[50:51], v[50:51], 0, s[16:17]
	v_mul_f32_e32 v54, 0x45800000, v52
	v_cndmask_b32_e32 v52, v52, v54, vcc
	v_pk_mul_f32 v[34:35], v[34:35], v[52:53] op_sel_hi:[1,0]
	v_pk_mul_f32 v[54:55], v[32:33], v[52:53] op_sel_hi:[1,0]
	v_cvt_pk_bf16_f32 v32, v34, v35
	v_pk_mul_f32 v[34:35], v[38:39], v[52:53] op_sel_hi:[1,0]
	v_pk_mul_f32 v[36:37], v[36:37], v[52:53] op_sel_hi:[1,0]
	v_cvt_pk_bf16_f32 v34, v34, v35
	v_cvt_pk_bf16_f32 v35, v36, v37
	v_pk_mul_f32 v[36:37], v[46:47], v[52:53] op_sel_hi:[1,0]
	v_pk_mul_f32 v[38:39], v[44:45], v[52:53] op_sel_hi:[1,0]
	v_cvt_pk_bf16_f32 v36, v36, v37
	v_cvt_pk_bf16_f32 v37, v38, v39
	v_pk_mul_f32 v[38:39], v[42:43], v[52:53] op_sel_hi:[1,0]
	v_pk_mul_f32 v[40:41], v[40:41], v[52:53] op_sel_hi:[1,0]
	v_cvt_pk_bf16_f32 v38, v38, v39
	v_cvt_pk_bf16_f32 v39, v40, v41
	v_lshl_add_u64 v[40:41], s[74:75], 0, v[48:49]
	v_add_co_u32_e32 v40, vcc, s22, v40
	v_cvt_pk_bf16_f32 v33, v54, v55
	s_nop 0
	v_addc_co_u32_e32 v41, vcc, 0, v41, vcc
	global_store_dwordx4 v[40:41], v[32:35], off
	global_store_dwordx4 v[40:41], v[36:39], off offset:1024
	s_waitcnt vmcnt(3)
	v_mov_b64_e32 v[46:47], v[22:23]
	v_mov_b64_e32 v[42:43], v[18:19]
	v_mov_b64_e32 v[38:39], v[30:31]
	v_mov_b64_e32 v[34:35], v[26:27]
	v_lshl_add_u64 v[48:49], v[48:49], 0, s[16:17]
	s_andn2_b64 vcc, exec, s[18:19]
	v_mov_b64_e32 v[44:45], v[20:21]
	v_mov_b64_e32 v[40:41], v[16:17]
	v_mov_b64_e32 v[36:37], v[28:29]
	v_mov_b64_e32 v[32:33], v[24:25]
	v_mov_b32_e32 v52, v72
	s_mov_b32 s0, s29
	s_cbranch_vccz .LBB0_710

.LBB0_708:
	v_pk_mul_f32 v[78:79], v[60:61], v[60:61]
	v_pk_mul_f32 v[80:81], v[58:59], v[58:59]
	v_pk_mul_f32 v[74:75], v[56:57], v[56:57]
	v_pk_mul_f32 v[76:77], v[54:55], v[54:55]
	v_pk_mov_b32 v[82:83], v[80:81], v[78:79] op_sel:[1,0]
	v_mov_b32_e32 v81, v79
	v_pk_add_f32 v[78:79], v[82:83], v[80:81]
	v_pk_mov_b32 v[80:81], v[76:77], v[74:75] op_sel:[1,0]
	v_mov_b32_e32 v77, v75
	v_pk_add_f32 v[74:75], v[80:81], v[76:77]
	v_pk_add_f32 v[78:79], v[78:79], v[78:79] op_sel_hi:[0,1]
	v_pk_add_f32 v[74:75], v[74:75], v[74:75] op_sel_hi:[0,1]
	v_mul_f32_e32 v74, v44, v44
	v_pk_fma_f32 v[76:77], v[44:45], v[44:45], v[74:75] op_sel_hi:[1,1,0]
	v_mul_f32_e32 v74, v46, v46
	v_pk_fma_f32 v[80:81], v[46:47], v[46:47], v[74:75] op_sel_hi:[1,1,0]
	v_mul_f32_e32 v76, v40, v40
	v_mul_f32_e32 v80, v41, v41
	v_mul_f32_e32 v78, v42, v42
	v_mul_f32_e32 v74, v43, v43
	v_pk_add_f32 v[76:77], v[76:77], v[80:81]
	v_pk_add_f32 v[74:75], v[78:79], v[74:75]
	v_lshlrev_b32_e32 v78, 16, v32
	v_pk_add_f32 v[74:75], v[76:77], v[74:75]
	v_lshlrev_b32_e32 v80, 16, v33
	v_add_f32_e32 v73, v74, v75
	ds_bpermute_b32 v74, v66, v73
	v_and_b32_e32 v81, 0xffff0000, v33
	v_lshlrev_b32_e32 v82, 16, v34
	v_lshlrev_b32_e32 v84, 16, v35
	v_and_b32_e32 v85, 0xffff0000, v35
	s_waitcnt lgkmcnt(0)
	v_add_f32_e32 v73, v73, v74
	ds_bpermute_b32 v74, v67, v73
	v_lshlrev_b32_e32 v76, 16, v38
	s_waitcnt lgkmcnt(0)
	v_add_f32_e32 v73, v73, v74
	ds_bpermute_b32 v75, v68, v73
	v_lshlrev_b32_e32 v74, 16, v36
	s_waitcnt lgkmcnt(0)
	v_add_f32_e32 v73, v73, v75
	ds_bpermute_b32 v77, v69, v73
	v_and_b32_e32 v75, 0xffff0000, v36
	v_lshlrev_b32_e32 v36, 16, v37
	v_and_b32_e32 v37, 0xffff0000, v37
	s_waitcnt lgkmcnt(0)
	v_add_f32_e32 v73, v73, v77
	ds_bpermute_b32 v79, v70, v73
	v_and_b32_e32 v77, 0xffff0000, v38
	v_lshlrev_b32_e32 v38, 16, v39
	v_and_b32_e32 v39, 0xffff0000, v39
	s_waitcnt lgkmcnt(0)
	v_add_f32_e32 v73, v73, v79
	ds_bpermute_b32 v83, v71, v73
	v_and_b32_e32 v79, 0xffff0000, v32
	s_waitcnt lgkmcnt(0)
	v_add_f32_e32 v32, v73, v83
	v_fmamk_f32 v32, v32, 0x3a800000, v62
	v_mul_f32_e32 v33, 0x4b800000, v32
	v_cmp_gt_f32_e32 vcc, s23, v32
	v_and_b32_e32 v83, 0xffff0000, v34
	s_nop 0
	v_cndmask_b32_e32 v32, v32, v33, vcc
	v_rsq_f32_e32 v32, v32
	s_nop 0
	v_mul_f32_e32 v33, 0x45800000, v32
	v_cndmask_b32_e32 v86, v32, v33, vcc
	v_pk_mul_f32 v[32:33], v[60:61], v[86:87] op_sel_hi:[1,0]
	v_pk_mul_f32 v[34:35], v[58:59], v[86:87] op_sel_hi:[1,0]
	v_pk_mul_f32 v[32:33], v[6:7], v[32:33]
	v_pk_mul_f32 v[34:35], v[4:5], v[34:35]
	v_pk_fma_f32 v[32:33], v[52:53], v[36:37], v[32:33] op_sel_hi:[0,1,1]
	v_pk_fma_f32 v[34:35], v[52:53], v[74:75], v[34:35] op_sel_hi:[0,1,1]
	v_pk_mul_f32 v[36:37], v[32:33], v[32:33]
	v_pk_mul_f32 v[58:59], v[34:35], v[34:35]
	v_pk_mul_f32 v[54:55], v[54:55], v[86:87] op_sel_hi:[1,0]
	v_pk_mov_b32 v[60:61], v[58:59], v[36:37] op_sel:[1,0]
	v_mov_b32_e32 v59, v37
	v_pk_add_f32 v[36:37], v[60:61], v[58:59]
	v_pk_mul_f32 v[54:55], v[0:1], v[54:55]
	v_pk_add_f32 v[58:59], v[36:37], v[36:37] op_sel_hi:[0,1]
	v_pk_mul_f32 v[36:37], v[56:57], v[86:87] op_sel_hi:[1,0]
	v_pk_mul_f32 v[44:45], v[44:45], v[86:87] op_sel_hi:[1,0]
	v_pk_mul_f32 v[36:37], v[2:3], v[36:37]
	v_pk_mul_f32 v[46:47], v[46:47], v[86:87] op_sel_hi:[1,0]
	v_pk_fma_f32 v[36:37], v[52:53], v[38:39], v[36:37] op_sel_hi:[0,1,1]
	v_pk_fma_f32 v[38:39], v[52:53], v[76:77], v[54:55] op_sel_hi:[0,1,1]
	v_pk_mul_f32 v[54:55], v[36:37], v[36:37]
	v_pk_mul_f32 v[56:57], v[38:39], v[38:39]
	v_pk_mul_f32 v[42:43], v[42:43], v[86:87] op_sel_hi:[1,0]
	v_pk_mov_b32 v[60:61], v[56:57], v[54:55] op_sel:[1,0]
	v_mov_b32_e32 v57, v55
	v_pk_add_f32 v[54:55], v[60:61], v[56:57]
	s_waitcnt vmcnt(5)
	v_pk_mul_f32 v[56:57], v[12:13], v[44:45]
	v_pk_add_f32 v[54:55], v[54:55], v[54:55] op_sel_hi:[0,1]
	v_pk_mul_f32 v[44:45], v[14:15], v[46:47]
	v_pk_fma_f32 v[46:47], v[52:53], v[78:79], v[56:57] op_sel_hi:[0,1,1]
	v_pk_fma_f32 v[44:45], v[52:53], v[80:81], v[44:45] op_sel_hi:[0,1,1]
	v_mul_f32_e32 v54, v46, v46
	v_pk_mul_f32 v[40:41], v[40:41], v[86:87] op_sel_hi:[1,0]
	v_pk_fma_f32 v[56:57], v[46:47], v[46:47], v[54:55] op_sel_hi:[1,1,0]
	v_mul_f32_e32 v54, v44, v44
	v_pk_mul_f32 v[74:75], v[8:9], v[40:41]
	v_pk_mul_f32 v[40:41], v[10:11], v[42:43]
	v_pk_fma_f32 v[60:61], v[44:45], v[44:45], v[54:55] op_sel_hi:[1,1,0]
	v_pk_fma_f32 v[40:41], v[52:53], v[84:85], v[40:41] op_sel_hi:[0,1,1]
	v_pk_fma_f32 v[42:43], v[52:53], v[82:83], v[74:75] op_sel_hi:[0,1,1]
	v_mul_f32_e32 v56, v42, v42
	v_mul_f32_e32 v60, v43, v43
	v_mul_f32_e32 v58, v40, v40
	v_mul_f32_e32 v54, v41, v41
	v_pk_add_f32 v[56:57], v[56:57], v[60:61]
	v_pk_add_f32 v[54:55], v[58:59], v[54:55]
	s_nop 0
	v_pk_add_f32 v[54:55], v[56:57], v[54:55]
	s_nop 0
	v_add_f32_e32 v52, v54, v55
	ds_bpermute_b32 v54, v66, v52
	s_waitcnt lgkmcnt(0)
	v_add_f32_e32 v52, v52, v54
	ds_bpermute_b32 v54, v67, v52
	s_waitcnt lgkmcnt(0)
	v_add_f32_e32 v52, v52, v54
	ds_bpermute_b32 v54, v68, v52
	s_waitcnt lgkmcnt(0)
	v_add_f32_e32 v52, v52, v54
	ds_bpermute_b32 v54, v69, v52
	s_waitcnt lgkmcnt(0)
	v_add_f32_e32 v52, v52, v54
	ds_bpermute_b32 v54, v70, v52
	s_waitcnt lgkmcnt(0)
	v_add_f32_e32 v52, v52, v54
	ds_bpermute_b32 v54, v71, v52
	s_waitcnt lgkmcnt(0)
	v_add_f32_e32 v52, v52, v54
	v_fmamk_f32 v52, v52, 0x3a800000, v62
	s_and_saveexec_b64 s[20:21], s[6:7]
	s_cbranch_execz .LBB0_702
	v_mul_f32_e32 v54, 0x4f800000, v52
	v_cmp_gt_f32_e32 vcc, s24, v52
	s_nop 1
	v_cndmask_b32_e32 v54, v52, v54, vcc
	v_sqrt_f32_e32 v55, v54
	s_nop 0
	v_add_u32_e32 v56, -1, v55
	v_fma_f32 v58, -v56, v55, v54
	v_add_u32_e32 v57, 1, v55
	v_cmp_ge_f32_e64 s[0:1], 0, v58
	s_nop 1
	v_cndmask_b32_e64 v56, v55, v56, s[0:1]
	v_fma_f32 v55, -v57, v55, v54
	v_cmp_lt_f32_e64 s[0:1], 0, v55
	s_nop 1
	v_cndmask_b32_e64 v55, v56, v57, s[0:1]
	v_mul_f32_e32 v56, 0x37800000, v55
	v_cndmask_b32_e32 v55, v55, v56, vcc
	v_cmp_class_f32_e32 vcc, v54, v63
	s_add_u32 s0, s74, s25
	s_addc_u32 s1, s75, s26
	v_cndmask_b32_e32 v54, v55, v54, vcc
	global_store_dword v53, v54, s[0:1]
	s_branch .LBB0_702

.LBB0_1618:
	s_or_b64 exec, exec, s[20:21]
	v_mul_f32_e32 v54, 0x4b800000, v52
	v_cmp_gt_f32_e32 vcc, s22, v52
	s_add_u32 s24, s24, s14
	s_addc_u32 s25, s25, s15
	v_cndmask_b32_e32 v52, v52, v54, vcc
	v_rsq_f32_e32 v52, v52
	s_add_u32 s26, s26, s14
	s_addc_u32 s27, s27, s15
	v_lshl_add_u64 v[50:51], v[50:51], 0, s[16:17]
	v_mul_f32_e32 v54, 0x45800000, v52
	v_cndmask_b32_e32 v52, v52, v54, vcc
	v_pk_mul_f32 v[34:35], v[34:35], v[52:53] op_sel_hi:[1,0]
	v_pk_mul_f32 v[54:55], v[32:33], v[52:53] op_sel_hi:[1,0]
	v_cvt_pk_bf16_f32 v32, v34, v35
	v_pk_mul_f32 v[34:35], v[38:39], v[52:53] op_sel_hi:[1,0]
	v_pk_mul_f32 v[36:37], v[36:37], v[52:53] op_sel_hi:[1,0]
	v_cvt_pk_bf16_f32 v34, v34, v35
	v_cvt_pk_bf16_f32 v35, v36, v37
	v_pk_mul_f32 v[36:37], v[46:47], v[52:53] op_sel_hi:[1,0]
	v_pk_mul_f32 v[38:39], v[44:45], v[52:53] op_sel_hi:[1,0]
	v_cvt_pk_bf16_f32 v36, v36, v37
	v_cvt_pk_bf16_f32 v37, v38, v39
	v_pk_mul_f32 v[38:39], v[42:43], v[52:53] op_sel_hi:[1,0]
	v_pk_mul_f32 v[40:41], v[40:41], v[52:53] op_sel_hi:[1,0]
	v_cvt_pk_bf16_f32 v38, v38, v39
	v_cvt_pk_bf16_f32 v39, v40, v41
	v_lshl_add_u64 v[40:41], s[74:75], 0, v[48:49]
	v_add_co_u32_e32 v40, vcc, s2, v40
	v_cvt_pk_bf16_f32 v33, v54, v55
	s_nop 0
	v_addc_co_u32_e32 v41, vcc, 0, v41, vcc
	global_store_dwordx4 v[40:41], v[32:35], off
	global_store_dwordx4 v[40:41], v[36:39], off offset:1024
	s_waitcnt vmcnt(3)
	v_mov_b64_e32 v[46:47], v[22:23]
	v_mov_b64_e32 v[42:43], v[18:19]
	v_mov_b64_e32 v[38:39], v[30:31]
	v_mov_b64_e32 v[34:35], v[26:27]
	v_lshl_add_u64 v[48:49], v[48:49], 0, s[16:17]
	s_andn2_b64 vcc, exec, s[18:19]
	v_mov_b64_e32 v[44:45], v[20:21]
	v_mov_b64_e32 v[40:41], v[16:17]
	v_mov_b64_e32 v[36:37], v[28:29]
	v_mov_b64_e32 v[32:33], v[24:25]
	v_mov_b32_e32 v52, v66
	s_mov_b32 s0, s28
	s_cbranch_vccz .LBB0_1626

.LBB0_1624:
	v_pk_mul_f32 v[72:73], v[60:61], v[60:61]
	v_pk_mul_f32 v[74:75], v[58:59], v[58:59]
	v_pk_mul_f32 v[68:69], v[56:57], v[56:57]
	v_pk_mul_f32 v[70:71], v[54:55], v[54:55]
	v_pk_mov_b32 v[76:77], v[74:75], v[72:73] op_sel:[1,0]
	v_mov_b32_e32 v75, v73
	v_pk_add_f32 v[72:73], v[76:77], v[74:75]
	v_pk_mov_b32 v[74:75], v[70:71], v[68:69] op_sel:[1,0]
	v_mov_b32_e32 v71, v69
	v_pk_add_f32 v[68:69], v[74:75], v[70:71]
	v_pk_add_f32 v[72:73], v[72:73], v[72:73] op_sel_hi:[0,1]
	v_pk_add_f32 v[68:69], v[68:69], v[68:69] op_sel_hi:[0,1]
	v_mul_f32_e32 v68, v44, v44
	v_pk_fma_f32 v[70:71], v[44:45], v[44:45], v[68:69] op_sel_hi:[1,1,0]
	v_mul_f32_e32 v68, v46, v46
	v_pk_fma_f32 v[74:75], v[46:47], v[46:47], v[68:69] op_sel_hi:[1,1,0]
	v_mul_f32_e32 v70, v40, v40
	v_mul_f32_e32 v74, v41, v41
	v_mul_f32_e32 v72, v42, v42
	v_mul_f32_e32 v68, v43, v43
	v_pk_add_f32 v[70:71], v[70:71], v[74:75]
	v_pk_add_f32 v[68:69], v[72:73], v[68:69]
	v_lshlrev_b32_e32 v72, 16, v32
	v_pk_add_f32 v[68:69], v[70:71], v[68:69]
	v_lshlrev_b32_e32 v74, 16, v33
	v_add_f32_e32 v67, v68, v69
	ds_bpermute_b32 v68, v176, v67
	v_and_b32_e32 v75, 0xffff0000, v33
	v_lshlrev_b32_e32 v76, 16, v34
	v_lshlrev_b32_e32 v78, 16, v35
	v_and_b32_e32 v79, 0xffff0000, v35
	s_waitcnt lgkmcnt(0)
	v_add_f32_e32 v67, v67, v68
	ds_bpermute_b32 v68, v177, v67
	v_lshlrev_b32_e32 v70, 16, v38
	s_waitcnt lgkmcnt(0)
	v_add_f32_e32 v67, v67, v68
	ds_bpermute_b32 v69, v178, v67
	v_lshlrev_b32_e32 v68, 16, v36
	s_waitcnt lgkmcnt(0)
	v_add_f32_e32 v67, v67, v69
	ds_bpermute_b32 v71, v179, v67
	v_and_b32_e32 v69, 0xffff0000, v36
	v_lshlrev_b32_e32 v36, 16, v37
	v_and_b32_e32 v37, 0xffff0000, v37
	s_waitcnt lgkmcnt(0)
	v_add_f32_e32 v67, v67, v71
	ds_bpermute_b32 v73, v180, v67
	v_and_b32_e32 v71, 0xffff0000, v38
	v_lshlrev_b32_e32 v38, 16, v39
	v_and_b32_e32 v39, 0xffff0000, v39
	s_waitcnt lgkmcnt(0)
	v_add_f32_e32 v67, v67, v73
	ds_bpermute_b32 v77, v181, v67
	v_and_b32_e32 v73, 0xffff0000, v32
	s_waitcnt lgkmcnt(0)
	v_add_f32_e32 v32, v67, v77
	v_fmamk_f32 v32, v32, 0x3a800000, v62
	v_mul_f32_e32 v33, 0x4b800000, v32
	v_cmp_gt_f32_e32 vcc, s22, v32
	v_and_b32_e32 v77, 0xffff0000, v34
	s_nop 0
	v_cndmask_b32_e32 v32, v32, v33, vcc
	v_rsq_f32_e32 v32, v32
	s_nop 0
	v_mul_f32_e32 v33, 0x45800000, v32
	v_cndmask_b32_e32 v80, v32, v33, vcc
	v_pk_mul_f32 v[32:33], v[60:61], v[80:81] op_sel_hi:[1,0]
	v_pk_mul_f32 v[34:35], v[58:59], v[80:81] op_sel_hi:[1,0]
	v_pk_mul_f32 v[32:33], v[6:7], v[32:33]
	v_pk_mul_f32 v[34:35], v[4:5], v[34:35]
	v_pk_fma_f32 v[32:33], v[52:53], v[36:37], v[32:33] op_sel_hi:[0,1,1]
	v_pk_fma_f32 v[34:35], v[52:53], v[68:69], v[34:35] op_sel_hi:[0,1,1]
	v_pk_mul_f32 v[36:37], v[32:33], v[32:33]
	v_pk_mul_f32 v[58:59], v[34:35], v[34:35]
	v_pk_mul_f32 v[54:55], v[54:55], v[80:81] op_sel_hi:[1,0]
	v_pk_mov_b32 v[60:61], v[58:59], v[36:37] op_sel:[1,0]
	v_mov_b32_e32 v59, v37
	v_pk_add_f32 v[36:37], v[60:61], v[58:59]
	v_pk_mul_f32 v[54:55], v[0:1], v[54:55]
	v_pk_add_f32 v[58:59], v[36:37], v[36:37] op_sel_hi:[0,1]
	v_pk_mul_f32 v[36:37], v[56:57], v[80:81] op_sel_hi:[1,0]
	v_pk_mul_f32 v[44:45], v[44:45], v[80:81] op_sel_hi:[1,0]
	v_pk_mul_f32 v[36:37], v[2:3], v[36:37]
	v_pk_mul_f32 v[46:47], v[46:47], v[80:81] op_sel_hi:[1,0]
	v_pk_fma_f32 v[36:37], v[52:53], v[38:39], v[36:37] op_sel_hi:[0,1,1]
	v_pk_fma_f32 v[38:39], v[52:53], v[70:71], v[54:55] op_sel_hi:[0,1,1]
	v_pk_mul_f32 v[54:55], v[36:37], v[36:37]
	v_pk_mul_f32 v[56:57], v[38:39], v[38:39]
	v_pk_mul_f32 v[42:43], v[42:43], v[80:81] op_sel_hi:[1,0]
	v_pk_mov_b32 v[60:61], v[56:57], v[54:55] op_sel:[1,0]
	v_mov_b32_e32 v57, v55
	v_pk_add_f32 v[54:55], v[60:61], v[56:57]
	s_waitcnt vmcnt(5)
	v_pk_mul_f32 v[56:57], v[12:13], v[44:45]
	v_pk_add_f32 v[54:55], v[54:55], v[54:55] op_sel_hi:[0,1]
	v_pk_mul_f32 v[44:45], v[14:15], v[46:47]
	v_pk_fma_f32 v[46:47], v[52:53], v[72:73], v[56:57] op_sel_hi:[0,1,1]
	v_pk_fma_f32 v[44:45], v[52:53], v[74:75], v[44:45] op_sel_hi:[0,1,1]
	v_mul_f32_e32 v54, v46, v46
	v_pk_mul_f32 v[40:41], v[40:41], v[80:81] op_sel_hi:[1,0]
	v_pk_fma_f32 v[56:57], v[46:47], v[46:47], v[54:55] op_sel_hi:[1,1,0]
	v_mul_f32_e32 v54, v44, v44
	v_pk_mul_f32 v[68:69], v[8:9], v[40:41]
	v_pk_mul_f32 v[40:41], v[10:11], v[42:43]
	v_pk_fma_f32 v[60:61], v[44:45], v[44:45], v[54:55] op_sel_hi:[1,1,0]
	v_pk_fma_f32 v[40:41], v[52:53], v[78:79], v[40:41] op_sel_hi:[0,1,1]
	v_pk_fma_f32 v[42:43], v[52:53], v[76:77], v[68:69] op_sel_hi:[0,1,1]
	v_mul_f32_e32 v56, v42, v42
	v_mul_f32_e32 v60, v43, v43
	v_mul_f32_e32 v58, v40, v40
	v_mul_f32_e32 v54, v41, v41
	v_pk_add_f32 v[56:57], v[56:57], v[60:61]
	v_pk_add_f32 v[54:55], v[58:59], v[54:55]
	s_nop 0
	v_pk_add_f32 v[54:55], v[56:57], v[54:55]
	s_nop 0
	v_add_f32_e32 v52, v54, v55
	ds_bpermute_b32 v54, v176, v52
	s_waitcnt lgkmcnt(0)
	v_add_f32_e32 v52, v52, v54
	ds_bpermute_b32 v54, v177, v52
	s_waitcnt lgkmcnt(0)
	v_add_f32_e32 v52, v52, v54
	ds_bpermute_b32 v54, v178, v52
	s_waitcnt lgkmcnt(0)
	v_add_f32_e32 v52, v52, v54
	ds_bpermute_b32 v54, v179, v52
	s_waitcnt lgkmcnt(0)
	v_add_f32_e32 v52, v52, v54
	ds_bpermute_b32 v54, v180, v52
	s_waitcnt lgkmcnt(0)
	v_add_f32_e32 v52, v52, v54
	ds_bpermute_b32 v54, v181, v52
	s_waitcnt lgkmcnt(0)
	v_add_f32_e32 v52, v52, v54
	v_fmamk_f32 v52, v52, 0x3a800000, v62
	s_and_saveexec_b64 s[20:21], s[6:7]
	s_cbranch_execz .LBB0_1618
	v_mul_f32_e32 v54, 0x4f800000, v52
	v_cmp_gt_f32_e32 vcc, s23, v52
	s_nop 1
	v_cndmask_b32_e32 v54, v52, v54, vcc
	v_sqrt_f32_e32 v55, v54
	s_nop 0
	v_add_u32_e32 v56, -1, v55
	v_fma_f32 v58, -v56, v55, v54
	v_add_u32_e32 v57, 1, v55
	v_cmp_ge_f32_e64 s[0:1], 0, v58
	s_nop 1
	v_cndmask_b32_e64 v56, v55, v56, s[0:1]
	v_fma_f32 v55, -v57, v55, v54
	v_cmp_lt_f32_e64 s[0:1], 0, v55
	s_nop 1
	v_cndmask_b32_e64 v55, v56, v57, s[0:1]
	v_mul_f32_e32 v56, 0x37800000, v55
	v_cndmask_b32_e32 v55, v55, v56, vcc
	v_cmp_class_f32_e32 vcc, v54, v63
	s_add_u32 s0, s74, s24
	s_addc_u32 s1, s75, s25
	v_cndmask_b32_e32 v54, v55, v54, vcc
	global_store_dword v53, v54, s[0:1]
	s_branch .LBB0_1618

.LBB0_1917:
	v_pk_mul_f32 v[70:71], v[62:63], v[62:63]
	v_pk_mul_f32 v[72:73], v[60:61], v[60:61]
	v_pk_mul_f32 v[66:67], v[58:59], v[58:59]
	v_pk_mul_f32 v[68:69], v[56:57], v[56:57]
	v_pk_mov_b32 v[74:75], v[72:73], v[70:71] op_sel:[1,0]
	v_mov_b32_e32 v73, v71
	v_pk_add_f32 v[70:71], v[74:75], v[72:73]
	v_pk_mov_b32 v[72:73], v[68:69], v[66:67] op_sel:[1,0]
	v_mov_b32_e32 v69, v67
	v_pk_add_f32 v[66:67], v[72:73], v[68:69]
	v_pk_add_f32 v[70:71], v[70:71], v[70:71] op_sel_hi:[0,1]
	v_pk_add_f32 v[66:67], v[66:67], v[66:67] op_sel_hi:[0,1]
	v_mul_f32_e32 v66, v44, v44
	v_pk_fma_f32 v[68:69], v[44:45], v[44:45], v[66:67] op_sel_hi:[1,1,0]
	v_mul_f32_e32 v66, v46, v46
	v_pk_fma_f32 v[72:73], v[46:47], v[46:47], v[66:67] op_sel_hi:[1,1,0]
	v_mul_f32_e32 v68, v40, v40
	v_mul_f32_e32 v72, v41, v41
	v_mul_f32_e32 v70, v42, v42
	v_mul_f32_e32 v66, v43, v43
	v_pk_add_f32 v[68:69], v[68:69], v[72:73]
	v_pk_add_f32 v[66:67], v[70:71], v[66:67]
	v_and_b32_e32 v73, 0xffff0000, v17
	v_pk_add_f32 v[66:67], v[68:69], v[66:67]
	v_lshlrev_b32_e32 v74, 16, v18
	v_add_f32_e32 v66, v66, v67
	ds_bpermute_b32 v67, v176, v66
	v_and_b32_e32 v77, 0xffff0000, v19
	s_add_u32 s13, s13, s4
	s_addc_u32 s14, s14, s5
	v_lshl_add_u64 v[54:55], v[54:55], 0, s[6:7]
	s_waitcnt lgkmcnt(0)
	v_add_f32_e32 v66, v66, v67
	ds_bpermute_b32 v67, v177, v66
	s_mov_b32 s0, s15
	s_waitcnt lgkmcnt(0)
	v_add_f32_e32 v67, v66, v67
	ds_bpermute_b32 v68, v178, v67
	v_lshlrev_b32_e32 v66, 16, v28
	s_waitcnt lgkmcnt(0)
	v_add_f32_e32 v69, v67, v68
	ds_bpermute_b32 v70, v179, v69
	v_and_b32_e32 v67, 0xffff0000, v28
	v_lshlrev_b32_e32 v28, 16, v29
	v_and_b32_e32 v29, 0xffff0000, v29
	v_lshlrev_b32_e32 v68, 16, v30
	s_waitcnt lgkmcnt(0)
	v_add_f32_e32 v71, v69, v70
	ds_bpermute_b32 v72, v180, v71
	v_lshlrev_b32_e32 v70, 16, v16
	v_and_b32_e32 v69, 0xffff0000, v30
	v_lshlrev_b32_e32 v30, 16, v31
	v_and_b32_e32 v31, 0xffff0000, v31
	s_waitcnt lgkmcnt(0)
	v_add_f32_e32 v75, v71, v72
	ds_bpermute_b32 v76, v181, v75
	v_and_b32_e32 v71, 0xffff0000, v16
	v_lshlrev_b32_e32 v72, 16, v17
	s_waitcnt lgkmcnt(0)
	v_add_f32_e32 v16, v75, v76
	v_fmamk_f32 v16, v16, 0x3a800000, v51
	v_mul_f32_e32 v17, 0x4b800000, v16
	v_cmp_gt_f32_e32 vcc, s12, v16
	v_and_b32_e32 v75, 0xffff0000, v18
	v_lshlrev_b32_e32 v76, 16, v19
	v_cndmask_b32_e32 v16, v16, v17, vcc
	v_rsq_f32_e32 v16, v16
	s_nop 0
	v_mul_f32_e32 v17, 0x45800000, v16
	v_cndmask_b32_e32 v78, v16, v17, vcc
	v_pk_mul_f32 v[16:17], v[62:63], v[78:79] op_sel_hi:[1,0]
	v_pk_mul_f32 v[18:19], v[60:61], v[78:79] op_sel_hi:[1,0]
	v_pk_mul_f32 v[16:17], v[6:7], v[16:17]
	v_pk_mul_f32 v[60:61], v[4:5], v[18:19]
	v_pk_fma_f32 v[18:19], v[50:51], v[28:29], v[16:17] op_sel_hi:[0,1,1]
	v_pk_mul_f32 v[28:29], v[58:59], v[78:79] op_sel_hi:[1,0]
	v_pk_mul_f32 v[56:57], v[56:57], v[78:79] op_sel_hi:[1,0]
	v_pk_mul_f32 v[46:47], v[46:47], v[78:79] op_sel_hi:[1,0]
	v_pk_mul_f32 v[44:45], v[44:45], v[78:79] op_sel_hi:[1,0]
	v_pk_mul_f32 v[42:43], v[42:43], v[78:79] op_sel_hi:[1,0]
	v_pk_mul_f32 v[40:41], v[40:41], v[78:79] op_sel_hi:[1,0]
	v_pk_mul_f32 v[56:57], v[0:1], v[56:57]
	v_pk_mul_f32 v[28:29], v[2:3], v[28:29]
	s_waitcnt vmcnt(5)
	v_pk_mul_f32 v[44:45], v[12:13], v[44:45]
	v_pk_mul_f32 v[46:47], v[14:15], v[46:47]
	v_pk_mul_f32 v[40:41], v[8:9], v[40:41]
	v_pk_mul_f32 v[42:43], v[10:11], v[42:43]
	v_pk_fma_f32 v[16:17], v[50:51], v[66:67], v[60:61] op_sel_hi:[0,1,1]
	v_pk_fma_f32 v[30:31], v[50:51], v[30:31], v[28:29] op_sel_hi:[0,1,1]
	v_pk_fma_f32 v[28:29], v[50:51], v[68:69], v[56:57] op_sel_hi:[0,1,1]
	v_pk_fma_f32 v[46:47], v[50:51], v[72:73], v[46:47] op_sel_hi:[0,1,1]
	v_pk_fma_f32 v[44:45], v[50:51], v[70:71], v[44:45] op_sel_hi:[0,1,1]
	v_pk_fma_f32 v[42:43], v[50:51], v[76:77], v[42:43] op_sel_hi:[0,1,1]
	v_pk_fma_f32 v[40:41], v[50:51], v[74:75], v[40:41] op_sel_hi:[0,1,1]
	global_store_dwordx4 v[52:53], v[16:19], off offset:-2064
	global_store_dwordx4 v[52:53], v[28:31], off offset:-2048
	global_store_dwordx4 v[52:53], v[44:47], off offset:-16
	global_store_dwordx4 v[52:53], v[40:43], off
	s_waitcnt vmcnt(4)
	v_mov_b64_e32 v[28:29], v[36:37]
	v_mov_b64_e32 v[46:47], v[26:27]
	v_mov_b64_e32 v[42:43], v[22:23]
	v_mov_b64_e32 v[16:17], v[32:33]
	v_lshl_add_u64 v[52:53], v[52:53], 0, s[2:3]
	s_andn2_b64 vcc, exec, s[8:9]
	v_mov_b64_e32 v[44:45], v[24:25]
	v_mov_b64_e32 v[40:41], v[20:21]
	v_mov_b64_e32 v[30:31], v[38:39]
	v_mov_b64_e32 v[18:19], v[34:35]
	v_mov_b32_e32 v50, v48
	s_cbranch_vccz .LBB0_1922
